# P2: four workgroup groups (cid bits 3-4) visit their 16 items rotated by 0/4/8/12
# speedup vs baseline: 1.0170x; 1.0070x over previous
.LBB0_536:
	v_readlane_b32 s0, v246, 4
	s_cmp_lt_i32 s0, 3
	v_readlane_b32 s1, v246, 5
	s_cselect_b64 s[4:5], -1, 0
	s_and_b64 s[0:1], s[4:5], s[2:3]
	s_xor_b64 s[0:1], s[0:1], -1
	s_cmpk_gt_i32 s30, 0xfff
	s_cselect_b64 s[2:3], -1, 0
	s_or_b64 s[0:1], s[2:3], s[0:1]
	s_and_b64 vcc, exec, s[0:1]
	v_writelane_b32 v246, s20, 62
	s_nop 1
	v_writelane_b32 v245, s22, 0
	v_writelane_b32 v246, s21, 63
	v_writelane_b32 v245, s23, 1
	s_cbranch_vccnz .LBB0_577
	v_writelane_b32 v245, s4, 2
	v_cmp_gt_u32_e64 s[0:1], 64, v202
	v_and_b32_e32 v40, 63, v202
	v_writelane_b32 v245, s5, 3
	v_writelane_b32 v245, s0, 4
	v_lshrrev_b32_e32 v44, 3, v202
	v_and_b32_e32 v16, 7, v202
	v_readlane_b32 s5, v246, 0
	v_writelane_b32 v245, s1, 5
	v_sub_co_u32_e64 v2, s[0:1], v44, v16
	v_lshlrev_b32_e32 v4, 2, v40
	v_cvt_f32_u32_e32 v134, v2
	v_add_u32_e32 v137, s5, v4
	v_and_b32_e32 v2, 0x3c0, v202
	v_lshl_add_u32 v138, v2, 2, v137
	v_xor_b32_e32 v2, 0x7f, v44
	v_cvt_f32_u32_e32 v142, v2
	v_add_u32_e32 v2, 0x200, v202
	v_bfe_u32 v17, v202, 4, 2
	v_lshrrev_b32_e32 v0, 4, v202
	v_mov_b32_e32 v1, 0xfffe2000
	v_lshrrev_b32_e32 v46, 3, v2
	v_lshlrev_b32_e32 v42, 3, v17
	v_bfe_u32 v18, v202, 2, 2
	v_and_or_b32 v41, v0, 60, v1
	v_mov_b32_e32 v1, s5
	s_movk_i32 s6, 0x90
	v_sub_u32_e32 v2, 0x7f, v46
	v_or_b32_e32 v6, v42, v18
	v_lshrrev_b32_e32 v9, 5, v202
	v_cvt_f32_i32_e32 v144, v2
	v_and_b32_e32 v5, 15, v202
	v_lshrrev_b32_e32 v2, 7, v202
	v_mad_u32_u24 v8, v6, s6, v1
	v_and_b32_e32 v10, 2, v9
	v_writelane_b32 v245, s0, 6
	v_lshl_add_u32 v7, v2, 5, v8
	v_lshlrev_b32_e32 v9, 5, v10
	v_lshlrev_b32_e32 v2, 10, v2
	v_lshlrev_b32_e32 v11, 8, v17
	v_lshl_or_b32 v10, v10, 4, v5
	v_writelane_b32 v245, s1, 7
	v_or3_b32 v48, v11, v2, v10
	s_movk_i32 s0, 0x80
	v_lshrrev_b32_e32 v15, 2, v202
	v_and_b32_e32 v2, 8, v202
	v_cmp_gt_u32_e64 s[0:1], s0, v202
	v_and_or_b32 v2, v15, 16, v2
	v_lshrrev_b32_e32 v146, 3, v2
	v_writelane_b32 v245, s0, 8
	v_lshlrev_b32_e32 v2, 2, v17
	v_or_b32_e32 v13, 2, v2
	v_writelane_b32 v245, s1, 9
	v_cmp_gt_u32_e64 s[0:1], v2, v16
	v_or_b32_e32 v12, 0x80, v16
	v_and_b32_e32 v19, 0xe0, v15
	v_writelane_b32 v245, s0, 10
	v_mad_u32_u24 v11, v5, s6, v1
	v_or_b32_e32 v147, v2, v19
	v_writelane_b32 v245, s1, 11
	v_cmp_lt_u32_e64 s[0:1], v2, v16
	v_or_b32_e32 v149, 2, v147
	v_or_b32_e32 v150, 3, v147
	v_writelane_b32 v245, s0, 12
	v_or_b32_e32 v151, 16, v147
	v_or_b32_e32 v152, 17, v147
	v_writelane_b32 v245, s1, 13
	v_cmp_gt_u32_e64 s[0:1], v13, v16
	v_or_b32_e32 v13, 3, v2
	v_or_b32_e32 v153, 18, v147
	v_writelane_b32 v245, s0, 14
	v_or_b32_e32 v154, 19, v147
	v_add_u32_e32 v155, 32, v147
	v_writelane_b32 v245, s1, 15
	v_cmp_gt_u32_e64 s[0:1], v13, v16
	v_or_b32_e32 v13, 0x81, v2
	v_add_u32_e32 v156, 33, v147
	v_writelane_b32 v245, s0, 16
	v_add_u32_e32 v157, 34, v147
	v_add_u32_e32 v158, 35, v147
	v_writelane_b32 v245, s1, 17
	v_cmp_gt_u32_e64 s[0:1], v13, v12
	v_or_b32_e32 v13, 0x82, v2
	v_add_u32_e32 v159, 48, v147
	v_writelane_b32 v245, s0, 18
	v_add_u32_e32 v160, 49, v147
	v_add_u32_e32 v161, 50, v147
	v_writelane_b32 v245, s1, 19
	v_cmp_gt_u32_e64 s[0:1], v13, v12
	v_or_b32_e32 v13, 0x83, v2
	v_add_u32_e32 v162, 51, v147
	v_writelane_b32 v245, s0, 20
	v_add_u32_e32 v163, 64, v147
	v_add_u32_e32 v164, 0x41, v147
	v_writelane_b32 v245, s1, 21
	v_cmp_gt_u32_e64 s[0:1], v13, v12
	v_add_u32_e32 v165, 0x42, v147
	v_add_u32_e32 v166, 0x43, v147
	v_writelane_b32 v245, s0, 22
	v_add_u32_e32 v167, 0x50, v147
	s_waitcnt vmcnt(0)
	v_add_u32_e32 v168, 0x51, v147
	v_writelane_b32 v245, s1, 23
	s_movk_i32 s0, 0x1ff
	v_cmp_lt_u32_e64 s[0:1], s0, v202
	v_add_u32_e32 v169, 0x52, v147
	v_add_u32_e32 v170, 0x53, v147
	v_writelane_b32 v245, s0, 24
	v_add_u32_e32 v171, 0x60, v147
	v_add_u32_e32 v172, 0x61, v147
	v_writelane_b32 v245, s1, 25
	s_movk_i32 s0, 0xf0
	v_and_or_b32 v54, v15, s0, v5
	v_or_b32_e32 v5, v19, v5
	v_mad_u32_u24 v15, v5, s6, v1
	v_add_u32_e32 v5, 0x80, v54
	v_cmp_gt_u32_e32 vcc, v147, v54
	v_cmp_le_u32_e64 s[0:1], v147, v5
	s_and_b64 s[0:1], vcc, s[0:1]
	v_cmp_ge_u32_e32 vcc, v147, v54
	v_writelane_b32 v245, s0, 26
	v_add_u32_e32 v173, 0x62, v147
	v_add_u32_e32 v174, 0x63, v147
	v_writelane_b32 v245, s1, 27
	v_cmp_lt_u32_e64 s[0:1], v147, v5
	s_and_b64 s[0:1], vcc, s[0:1]
	v_cmp_gt_u32_e32 vcc, v149, v54
	v_writelane_b32 v245, s0, 28
	v_add_u32_e32 v175, 0x70, v147
	v_add_u32_e32 v176, 0x71, v147
	v_writelane_b32 v245, s1, 29
	v_cmp_le_u32_e64 s[0:1], v149, v5
	s_and_b64 s[0:1], vcc, s[0:1]
	v_cmp_gt_u32_e32 vcc, v150, v54
	v_writelane_b32 v245, s0, 30
	v_add_u32_e32 v177, 0x72, v147
	v_add_u32_e32 v178, 0x73, v147
	v_writelane_b32 v245, s1, 31
	v_cmp_le_u32_e64 s[0:1], v150, v5
	s_and_b64 s[0:1], vcc, s[0:1]
	v_cmp_gt_u32_e32 vcc, v151, v54
	v_writelane_b32 v245, s0, 32
	v_add_u32_e32 v19, 0x80, v147
	s_mov_b64 s[16:17], s[20:21]
	v_writelane_b32 v245, s1, 33
	v_cmp_le_u32_e64 s[0:1], v151, v5
	s_and_b64 s[0:1], vcc, s[0:1]
	v_cmp_gt_u32_e32 vcc, v152, v54
	v_writelane_b32 v245, s0, 34
	s_mov_b64 s[18:19], s[22:23]
	v_mov_b32_e32 v43, 0
	v_writelane_b32 v245, s1, 35
	v_cmp_le_u32_e64 s[0:1], v152, v5
	s_and_b64 s[0:1], vcc, s[0:1]
	v_cmp_gt_u32_e32 vcc, v153, v54
	v_writelane_b32 v245, s0, 36
	v_readlane_b32 s44, v246, 6
	v_or_b32_e32 v12, v2, v18
	v_writelane_b32 v245, s1, 37
	v_cmp_le_u32_e64 s[0:1], v153, v5
	s_and_b64 s[0:1], vcc, s[0:1]
	v_cmp_gt_u32_e32 vcc, v154, v54
	v_writelane_b32 v245, s0, 38
	v_readlane_b32 s45, v246, 7
	v_readlane_b32 s46, v246, 8
	v_writelane_b32 v245, s1, 39
	v_cmp_le_u32_e64 s[0:1], v154, v5
	s_and_b64 s[0:1], vcc, s[0:1]
	v_cmp_gt_u32_e32 vcc, v155, v54
	v_writelane_b32 v245, s0, 40
	v_readlane_b32 s47, v246, 9
	v_readlane_b32 s48, v246, 10
	v_writelane_b32 v245, s1, 41
	v_cmp_le_u32_e64 s[0:1], v155, v5
	s_and_b64 s[0:1], vcc, s[0:1]
	v_cmp_gt_u32_e32 vcc, v156, v54
	v_writelane_b32 v245, s0, 42
	v_readlane_b32 s49, v246, 11
	v_readlane_b32 s50, v246, 12
	v_writelane_b32 v245, s1, 43
	v_cmp_le_u32_e64 s[0:1], v156, v5
	s_and_b64 s[0:1], vcc, s[0:1]
	v_cmp_gt_u32_e32 vcc, v157, v54
	v_writelane_b32 v245, s0, 44
	v_readlane_b32 s51, v246, 13
	v_readlane_b32 s52, v246, 14
	v_writelane_b32 v245, s1, 45
	v_cmp_le_u32_e64 s[0:1], v157, v5
	s_and_b64 s[0:1], vcc, s[0:1]
	v_cmp_gt_u32_e32 vcc, v158, v54
	v_writelane_b32 v245, s0, 46
	v_readlane_b32 s53, v246, 15
	v_readlane_b32 s54, v246, 16
	v_writelane_b32 v245, s1, 47
	v_cmp_le_u32_e64 s[0:1], v158, v5
	s_and_b64 s[0:1], vcc, s[0:1]
	v_cmp_gt_u32_e32 vcc, v159, v54
	v_writelane_b32 v245, s0, 48
	v_readlane_b32 s55, v246, 17
	v_readlane_b32 s56, v246, 18
	v_writelane_b32 v245, s1, 49
	v_cmp_le_u32_e64 s[0:1], v159, v5
	s_and_b64 s[0:1], vcc, s[0:1]
	v_cmp_gt_u32_e32 vcc, v160, v54
	v_writelane_b32 v245, s0, 50
	v_readlane_b32 s57, v246, 19
	v_readlane_b32 s58, v246, 20
	v_writelane_b32 v245, s1, 51
	v_cmp_le_u32_e64 s[0:1], v160, v5
	s_and_b64 s[0:1], vcc, s[0:1]
	v_cmp_gt_u32_e32 vcc, v161, v54
	v_writelane_b32 v245, s0, 52
	v_readlane_b32 s59, v246, 21
	v_lshlrev_b32_e32 v20, 3, v40
	v_writelane_b32 v245, s1, 53
	v_cmp_le_u32_e64 s[0:1], v161, v5
	s_and_b64 s[0:1], vcc, s[0:1]
	v_cmp_gt_u32_e32 vcc, v162, v54
	v_writelane_b32 v245, s0, 54
	s_waitcnt lgkmcnt(0)
	v_mov_b32_e32 v21, v43
	v_lshrrev_b32_e32 v0, 6, v202
	v_writelane_b32 v245, s1, 55
	v_cmp_le_u32_e64 s[0:1], v162, v5
	s_and_b64 s[0:1], vcc, s[0:1]
	v_cmp_gt_u32_e32 vcc, v163, v54
	v_writelane_b32 v245, s0, 56
	v_or_b32_e32 v45, 0x8000, v0
	v_lshlrev_b32_e32 v135, 9, v0
	v_writelane_b32 v245, s1, 57
	v_cmp_le_u32_e64 s[0:1], v163, v5
	s_and_b64 s[0:1], vcc, s[0:1]
	v_cmp_gt_u32_e32 vcc, v164, v54
	v_writelane_b32 v245, s0, 58
	v_lshl_add_u32 v136, v0, 5, s5
	v_lshlrev_b32_e32 v3, 11, v0
	v_writelane_b32 v245, s1, 59
	v_cmp_le_u32_e64 s[0:1], v164, v5
	s_and_b64 s[0:1], vcc, s[0:1]
	v_cmp_gt_u32_e32 vcc, v165, v54
	v_writelane_b32 v245, s0, 60
	v_add_u32_e32 v0, 1, v0
	v_cvt_f32_u32_e32 v139, v0
	v_writelane_b32 v245, s1, 61
	v_cmp_le_u32_e64 s[0:1], v165, v5
	s_and_b64 s[0:1], vcc, s[0:1]
	v_cmp_gt_u32_e32 vcc, v166, v54
	v_writelane_b32 v245, s0, 62
	v_lshlrev_b32_e32 v0, 4, v16
	v_mad_u32_u24 v12, v12, s6, v1
	v_writelane_b32 v245, s1, 63
	v_cmp_le_u32_e64 s[0:1], v166, v5
	s_and_b64 s[0:1], vcc, s[0:1]
	v_cmp_gt_u32_e32 vcc, v167, v54
	v_writelane_b32 v244, s0, 0
	v_add_u32_e32 v141, s5, v0
	v_lshlrev_b32_e32 v6, 3, v202
	v_writelane_b32 v244, s1, 1
	v_cmp_le_u32_e64 s[0:1], v167, v5
	s_and_b64 s[0:1], vcc, s[0:1]
	v_cmp_gt_u32_e32 vcc, v168, v54
	v_writelane_b32 v244, s0, 2
	v_add_u32_e32 v14, 0x600, v202
	v_and_b32_e32 v6, 24, v6
	v_writelane_b32 v244, s1, 3
	v_cmp_le_u32_e64 s[0:1], v168, v5
	s_and_b64 s[0:1], vcc, s[0:1]
	v_cmp_gt_u32_e32 vcc, v169, v54
	v_writelane_b32 v244, s0, 4
	v_or_b32_e32 v50, 0x80, v44
	v_lshrrev_b32_e32 v52, 3, v14
	v_writelane_b32 v244, s1, 5
	v_cmp_le_u32_e64 s[0:1], v169, v5
	s_and_b64 s[0:1], vcc, s[0:1]
	v_cmp_gt_u32_e32 vcc, v170, v54
	v_writelane_b32 v244, s0, 6
	v_lshl_add_u32 v133, v16, 8, s5
	v_lshlrev_b32_e32 v140, 3, v16
	v_writelane_b32 v244, s1, 7
	v_cmp_le_u32_e64 s[0:1], v170, v5
	s_and_b64 s[0:1], vcc, s[0:1]
	v_cmp_gt_u32_e32 vcc, v171, v54
	v_writelane_b32 v244, s0, 8
	v_add_u32_e32 v8, v8, v6
	v_and_b32_e32 v10, 48, v202
	v_writelane_b32 v244, s1, 9
	v_cmp_le_u32_e64 s[0:1], v171, v5
	s_and_b64 s[0:1], vcc, s[0:1]
	v_cmp_gt_u32_e32 vcc, v172, v54
	v_writelane_b32 v244, s0, 10
	v_mul_u32_u24_e32 v13, 0x90, v50
	v_mul_u32_u24_e32 v14, 0x90, v52
	v_writelane_b32 v244, s1, 11
	v_cmp_le_u32_e64 s[0:1], v172, v5
	s_and_b64 s[0:1], vcc, s[0:1]
	v_cmp_gt_u32_e32 vcc, v173, v54
	v_writelane_b32 v244, s0, 12
	v_lshl_add_u32 v55, v202, 2, s5
	v_lshl_add_u32 v132, v44, 8, s5
	v_writelane_b32 v244, s1, 13
	v_cmp_le_u32_e64 s[0:1], v173, v5
	s_and_b64 s[0:1], vcc, s[0:1]
	v_cmp_gt_u32_e32 vcc, v174, v54
	v_writelane_b32 v244, s0, 14
	v_mul_u32_u24_e32 v143, 0x90, v44
	v_mul_u32_u24_e32 v145, 0x90, v46
	v_writelane_b32 v244, s1, 15
	v_cmp_le_u32_e64 s[0:1], v174, v5
	s_and_b64 s[0:1], vcc, s[0:1]
	v_cmp_gt_u32_e32 vcc, v175, v54
	v_writelane_b32 v244, s0, 16
	v_mov_b32_e32 v49, v43
	v_mov_b32_e32 v47, v43
	v_writelane_b32 v244, s1, 17
	v_cmp_le_u32_e64 s[0:1], v175, v5
	s_and_b64 s[0:1], vcc, s[0:1]
	v_cmp_gt_u32_e32 vcc, v176, v54
	v_writelane_b32 v244, s0, 18
	v_mov_b32_e32 v51, v43
	v_mov_b32_e32 v53, v43
	v_writelane_b32 v244, s1, 19
	v_cmp_le_u32_e64 s[0:1], v176, v5
	s_and_b64 s[0:1], vcc, s[0:1]
	v_cmp_gt_u32_e32 vcc, v177, v54
	v_writelane_b32 v244, s0, 20
	v_or_b32_e32 v148, 1, v147
	v_or_b32_e32 v179, 0x8000, v16
	v_writelane_b32 v244, s1, 21
	v_cmp_le_u32_e64 s[0:1], v177, v5
	s_and_b64 s[0:1], vcc, s[0:1]
	v_cmp_gt_u32_e32 vcc, v178, v54
	v_writelane_b32 v244, s0, 22
	v_or_b32_e32 v78, 16, v48
	v_mov_b32_e32 v79, v43
	v_writelane_b32 v244, s1, 23
	v_cmp_le_u32_e64 s[0:1], v178, v5
	s_and_b64 s[0:1], vcc, s[0:1]
	v_cmp_gt_u32_e32 vcc, v19, v54
	v_writelane_b32 v244, s0, 24
	v_add_u32_e32 v19, 0x81, v147
	v_add_u32_e32 v180, -8, v44
	v_writelane_b32 v244, s1, 25
	v_cmp_le_u32_e64 s[0:1], v147, v54
	s_and_b64 s[0:1], vcc, s[0:1]
	v_cmp_gt_u32_e32 vcc, v19, v54
	v_writelane_b32 v244, s0, 26
	v_lshl_or_b32 v181, v44, 7, v140
	v_mov_b32_e32 v183, 0x358637bd
	v_writelane_b32 v244, s1, 27
	v_cmp_le_u32_e64 s[0:1], v19, v5
	s_and_b64 s[0:1], vcc, s[0:1]
	v_add_u32_e32 v19, 0x82, v147
	v_writelane_b32 v244, s0, 28
	v_cmp_gt_u32_e32 vcc, v19, v54
	v_add_u32_e32 v184, v137, v3
	v_writelane_b32 v244, s1, 29
	v_cmp_le_u32_e64 s[0:1], v19, v5
	s_and_b64 s[0:1], vcc, s[0:1]
	v_add_u32_e32 v19, 0x83, v147
	v_writelane_b32 v244, s0, 30
	v_cmp_gt_u32_e32 vcc, v19, v54
	v_add_u32_e32 v185, v7, v6
	v_writelane_b32 v244, s1, 31
	v_cmp_le_u32_e64 s[0:1], v19, v5
	v_add_u32_e32 v19, 0x90, v147
	s_and_b64 s[34:35], vcc, s[0:1]
	v_cmp_gt_u32_e32 vcc, v19, v54
	v_cmp_le_u32_e64 s[0:1], v19, v5
	v_add_u32_e32 v19, 0x91, v147
	s_and_b64 s[20:21], vcc, s[0:1]
	v_cmp_gt_u32_e32 vcc, v19, v54
	v_cmp_le_u32_e64 s[0:1], v19, v5
	v_add_u32_e32 v19, 0x92, v147
	s_and_b64 s[22:23], vcc, s[0:1]
	v_cmp_gt_u32_e32 vcc, v19, v54
	v_cmp_le_u32_e64 s[0:1], v19, v5
	v_add_u32_e32 v19, 0x93, v147
	s_and_b64 s[2:3], vcc, s[0:1]
	v_cmp_le_u32_e64 s[0:1], v19, v5
	v_or_b32_e32 v5, v147, v18
	v_mad_u32_u24 v18, v5, s6, v1
	v_mov_b32_e32 v5, v43
	v_lshl_add_u64 v[56:57], s[54:55], 0, v[4:5]
	v_readlane_b32 s44, v246, 38
	v_readlane_b32 s48, v246, 42
	v_readlane_b32 s49, v246, 43
	v_cmp_gt_u32_e32 vcc, v19, v54
	v_readlane_b32 s50, v246, 44
	v_readlane_b32 s51, v246, 45
	s_mov_b64 s[12:13], s[48:49]
	s_and_b64 s[10:11], vcc, s[0:1]
	s_mov_b64 s[14:15], s[50:51]
	v_lshl_add_u64 v[22:23], s[18:19], 0, v[4:5]
	s_mov_b64 s[0:1], 0x190cc000
	v_lshl_add_u64 v[58:59], s[14:15], 0, v[20:21]
	v_lshl_add_u64 v[60:61], s[12:13], 0, v[20:21]
	v_lshl_add_u64 v[62:63], v[22:23], 0, s[0:1]
	v_lshl_add_u64 v[20:21], s[16:17], 0, v[20:21]
	s_mov_b64 s[0:1], 0x8600000
	v_lshl_add_u64 v[64:65], v[20:21], 0, s[0:1]
	s_add_u32 s0, s18, 0x95a4000
	s_addc_u32 s1, s19, 0
	s_add_u32 s8, s18, 0xb6a4000
	s_addc_u32 s9, s19, 0
	v_writelane_b32 v244, s0, 32
	s_add_u32 s12, s18, 0xd7a4000
	s_addc_u32 s13, s19, 0
	v_writelane_b32 v244, s1, 33
	v_lshl_add_u64 v[4:5], s[16:17], 0, v[4:5]
	s_mov_b64 s[0:1], 0x9e00000
	v_lshl_add_u64 v[66:67], v[4:5], 0, s[0:1]
	s_add_u32 s0, s18, 0xf8a4000
	s_addc_u32 s1, s19, 0
	v_writelane_b32 v244, s0, 34
	v_mov_b32_e32 v1, v43
	v_lshl_add_u64 v[4:5], s[18:19], 0, v[0:1]
	v_writelane_b32 v244, s1, 35
	s_add_u32 s0, s18, 0x119a4400
	s_addc_u32 s1, s19, 0
	v_writelane_b32 v244, s0, 36
	v_add_u32_e32 v186, v8, v9
	s_mov_b32 s33, 0x3fb8aa3b
	v_writelane_b32 v244, s1, 37
	v_writelane_b32 v244, s8, 38
	s_add_u32 s0, s18, 0x15ba4000
	v_lshlrev_b32_e32 v82, 1, v42
	v_writelane_b32 v244, s9, 39
	v_writelane_b32 v244, s12, 40
	v_lshl_add_u64 v[68:69], s[8:9], 0, v[0:1]
	v_add_u32_e32 v187, v11, v10
	v_writelane_b32 v244, s13, 41
	v_writelane_b32 v244, s0, 42
	s_addc_u32 s0, s19, 0
	v_writelane_b32 v244, s0, 43
	s_mov_b64 s[0:1], 0x8524000
	v_lshl_add_u64 v[72:73], v[4:5], 0, s[0:1]
	s_mov_b64 s[0:1], 0x8d64000
	v_lshl_add_u64 v[74:75], v[4:5], 0, s[0:1]
	s_add_u32 s0, s16, 0x8e00000
	s_addc_u32 s1, s17, 0
	v_writelane_b32 v244, s0, 44
	v_lshlrev_b32_e32 v4, 4, v17
	v_mov_b32_e32 v5, v43
	v_writelane_b32 v244, s1, 45
	s_add_u32 s0, s16, 0x9600000
	s_addc_u32 s1, s17, 0
	v_writelane_b32 v244, s0, 46
	v_lshl_add_u64 v[70:71], s[12:13], 0, v[0:1]
	v_mul_lo_u32 v1, v44, s6
	v_writelane_b32 v244, s1, 47
	s_add_u32 s0, s18, 0x6424000
	s_addc_u32 s1, s19, 0
	s_add_u32 s8, s18, 0x119a4000
	s_addc_u32 s9, s19, 0
	v_writelane_b32 v244, s8, 48
	v_add3_u32 v182, v1, v0, s5
	v_mbcnt_lo_u32_b32 v0, -1, 0
	v_writelane_b32 v244, s9, 49
	v_writelane_b32 v244, s0, 50
	v_mbcnt_hi_u32_b32 v193, -1, v0
	v_and_b32_e32 v0, 64, v193
	v_writelane_b32 v244, s1, 51
	v_lshl_add_u64 v[80:81], s[0:1], 0, v[4:5]
	s_bfe_u32 s0, s30, 0x20003
	s_lshl_b32 s0, s0, 10
	s_add_i32 s30, s30, s0
	s_add_i32 s0, s30, 0xfffffe00
	s_bitcmp1_b32 s30, 0
	v_writelane_b32 v244, s0, 52
	s_cselect_b64 s[0:1], -1, 0
	v_writelane_b32 v244, s0, 54
	v_lshl_add_u64 v[76:77], s[8:9], 0, v[42:43]
	s_mov_b32 s17, 0
	v_writelane_b32 v244, s1, 55
	v_readlane_b32 s0, v246, 1
	v_readlane_b32 s1, v246, 2
	s_bitcmp1_b32 s0, 0
	s_cselect_b64 s[0:1], -1, 0
	v_writelane_b32 v244, s0, 56
	v_add_u32_e32 v188, v12, v6
	v_lshlrev_b32_e32 v84, 1, v2
	v_add_u32_e32 v189, v141, v13
	v_add_u32_e32 v190, v141, v14
	v_add_u32_e32 v191, v15, v10
	v_add_u32_e32 v192, v18, v6
	v_add_u32_e32 v194, 64, v0
	v_xor_b32_e32 v195, 1, v193
	v_xor_b32_e32 v196, 2, v193
	v_xor_b32_e32 v197, 4, v193
	v_xor_b32_e32 v198, 8, v193
	v_xor_b32_e32 v199, 16, v193
	v_xor_b32_e32 v200, 32, v193
	v_mov_b32_e32 v201, 0x42800000
	v_add_u32_e32 v203, 0x800, v133
	v_add_u32_e32 v204, 0x808, v133
	v_add_u32_e32 v205, 0x810, v133
	v_add_u32_e32 v206, 0x818, v133
	v_add_u32_e32 v207, 0x820, v133
	v_add_u32_e32 v208, 0x828, v133
	v_add_u32_e32 v209, 0x830, v133
	v_add_u32_e32 v210, 0x838, v133
	v_mov_b32_e32 v211, 0xf149f2ca
	s_mov_b32 s6, s30
	v_readlane_b32 s45, v246, 39
	v_readlane_b32 s46, v246, 40
	v_readlane_b32 s47, v246, 41
	v_readlane_b32 s52, v246, 46
	v_readlane_b32 s53, v246, 47
	v_readlane_b32 s54, v246, 48
	v_readlane_b32 s55, v246, 49
	v_readlane_b32 s56, v246, 50
	v_readlane_b32 s57, v246, 51
	v_readlane_b32 s58, v246, 52
	v_readlane_b32 s59, v246, 53
	v_writelane_b32 v244, s1, 57
	s_branch .LBB0_539

.Lp2_nowrap:
	s_nop 0
	v_writelane_b32 v244, s1, 52
	v_readlane_b32 s0, v244, 54
	v_readlane_b32 s4, v244, 56
	v_readlane_b32 s1, v244, 55
	v_readlane_b32 s5, v244, 57
	s_xor_b64 s[0:1], s[0:1], s[4:5]
	v_readlane_b32 s4, v246, 60
	v_writelane_b32 v244, s0, 54
	v_writelane_b32 v244, s1, 55
	s_bfe_u32 s5, s4, 0x20003
	s_lshl_b32 s5, s5, 10
	s_add_i32 s4, s4, s5
	s_cmp_lg_u32 s6, s4
	s_cbranch_scc0 .LBB0_576
